# retention state sweep tile body: K/V fragment ds_reads issued ahead with counted lgkmcnt
# baseline (speedup 1.0000x reference)
; __device__ __forceinline__ unsigned cvtpk(float lo, float hi) { f32x2_t v = {lo, hi}; bf16x2_t b = __builtin_convertvector(v, bf16x2_t); return __builtin_bit_cast(unsigned, b); }
; #define LAS __attribute__((address_space(3)))
; #define MFMA32(a, b, c) __builtin_amdgcn_mfma_f32_32x32x16_bf16((a), (b), (c), 0, 0, 0)
; DI void ret_state_sweep(LAS unsigned char* lds, const bf16_t* MX, const bf16_t* VT, bf16_t* ST, int b, int hh, int dir, float lg, int wave) {
;     ...
;         const LAS unsigned char* Kl = lds + cur * RBUF;
;         const LAS unsigned char* Vl = Kl + RK_BYTES;
;         const int kt = SW_KT(it), n = kt >> 2;
;         const int tqf = dir ? 256 * n : 256 * n + 255;
;         bf16x8 f4[4];
; #pragma unroll
;         for (int kb = 0; kb < 2; ++kb) {
;             f32x16 x;
; #pragma unroll
;             for (int i = 0; i < 16; ++i) x[i] = 0.f;
;             { bf16x8 af[8];
; #pragma unroll
;               for (int s = 0; s < 8; ++s) af[s] = *(const LAS bf16x8*)(Kl + kA + ((s * 32) ^ sx32) + kb * 8192);
; #pragma unroll
;               for (int s = 0; s < 8; ++s) x = MFMA32(af[s], qf[s], x); }
;             __builtin_amdgcn_sched_barrier(0);
;             const float d0 = dir ? (float)(kt * 64 + kb * 32 + 4 * h - tqf) : (float)(tqf - kt * 64 - kb * 32 - 4 * h);
; #pragma unroll
;             for (int i = 0; i < 16; ++i) { const float cr = (float)((i & 3) + 8 * (i >> 2)); x[i] *= __builtin_amdgcn_exp2f(lg * (dir ? d0 + cr : d0 - cr)); }
; #pragma unroll
;             for (int s2 = 0; s2 < 2; ++s2) {
;                 u32x4 pw; pw.x = cvtpk(x[8 * s2 + 0], x[8 * s2 + 1]); pw.y = cvtpk(x[8 * s2 + 2], x[8 * s2 + 3]); pw.z = cvtpk(x[8 * s2 + 4], x[8 * s2 + 5]); pw.w = cvtpk(x[8 * s2 + 6], x[8 * s2 + 7]);
;                 f4[2 * kb + s2] = __builtin_bit_cast(bf16x8, pw);
;             }
;             __builtin_amdgcn_sched_barrier(0);
;         }
; #pragma unroll
;         for (int f = 0; f < 4; ++f) {
;             const int vo = vA + ((f * 32) ^ mv16);
; #pragma unroll
;             for (int db = 0; db < 4; ++db) z[db] = MFMA32(f4[f], *(const LAS bf16x8*)(Vl + vo + db * 4096), z[db]);
.LBB0_137:
	s_mul_i32 s4, s39, 0xc000
	s_add_i32 s11, s4, 0
	v_add3_u32 v215, s11, v193, v196
	v_add_u32_e32 v207, v215, v194
	v_add_u32_e32 v206, v215, v123
	v_add_u32_e32 v214, v215, v197
	v_add_u32_e32 v209, v215, v198
	v_add_u32_e32 v213, v215, v199
	v_add_u32_e32 v208, v215, v200
	v_add_u32_e32 v212, v215, v201
	v_add_u32_e32 v215, v215, v202
	ds_read_b128 v[64:67], v207
	ds_read_b128 v[112:115], v206
	ds_read_b128 v[116:119], v214
	ds_read_b128 v[218:221], v209
	ds_read_b128 v[222:225], v213
	ds_read_b128 v[226:229], v208
	ds_read_b128 v[230:233], v212
	ds_read_b128 v[246:249], v215
	s_add_i32 s11, s25, s11
	v_add_u32_e32 v234, s11, v192
	v_add_u32_e32 v235, v234, v195
	v_add_u32_e32 v250, v234, v203
	v_add_u32_e32 v252, v234, v204
	v_add_u32_e32 v253, v234, v205
	s_lshr_b32 s4, s5, 2
	v_readlane_b32 s22, v254, 18
	s_sub_i32 s28, 7, s4
	v_readlane_b32 s23, v254, 19
	s_and_b64 s[14:15], s[22:23], exec
	s_cselect_b32 s4, s4, s28
	s_and_b32 s5, s5, 3
	s_lshl_b32 s61, s4, 8
	s_lshl_b32 s14, s5, 6
	s_or_b32 s14, s61, s14
	v_add_u32_e32 v216, s14, v122
	s_mov_b32 s68, 0
	s_waitcnt lgkmcnt(7)
	v_mfma_f32_32x32x16_bf16 v[64:79], v[64:67], v[80:83], 0
	s_waitcnt lgkmcnt(6)
	v_mfma_f32_32x32x16_bf16 v[64:79], v[112:115], v[84:87], v[64:79]
	v_subrev_u32_e32 v112, s61, v122
	v_add_u32_e32 v217, s14, v112
	s_waitcnt lgkmcnt(5)
	v_mfma_f32_32x32x16_bf16 v[64:79], v[116:119], v[88:91], v[64:79]
	s_waitcnt lgkmcnt(4)
	v_mfma_f32_32x32x16_bf16 v[64:79], v[218:221], v[92:95], v[64:79]
	ds_read_b128 v[218:221], v207 offset:8192
	s_waitcnt lgkmcnt(4)
	v_mfma_f32_32x32x16_bf16 v[64:79], v[222:225], v[96:99], v[64:79]
	ds_read_b128 v[222:225], v206 offset:8192
	s_waitcnt lgkmcnt(4)
	v_mfma_f32_32x32x16_bf16 v[64:79], v[226:229], v[100:103], v[64:79]
	ds_read_b128 v[226:229], v214 offset:8192
	s_waitcnt lgkmcnt(4)
	v_mfma_f32_32x32x16_bf16 v[64:79], v[230:233], v[104:107], v[64:79]
	ds_read_b128 v[230:233], v209 offset:8192
	s_waitcnt lgkmcnt(4)
	v_mfma_f32_32x32x16_bf16 v[64:79], v[246:249], v[108:111], v[64:79]
	ds_read_b128 v[246:249], v213 offset:8192
	s_andn2_b64 vcc, exec, s[22:23]
	s_cbranch_vccnz .LBB0_139
	s_or_b32 s14, s61, 0xff
	v_sub_u32_e32 v112, s14, v216
	s_brev_b32 s68, 1
	s_mov_b32 s62, -1.0
	s_mov_b32 s60, -2.0
	s_mov_b32 s55, 0xc0400000
	s_mov_b32 s52, 0xc1000000
	s_mov_b32 s49, 0xc1100000
	s_mov_b32 s48, 0xc1200000
	s_mov_b32 s47, 0xc1300000
	s_mov_b32 s46, 0xc1800000
	s_mov_b32 s43, 0xc1880000
	s_mov_b32 s41, 0xc1900000
	s_mov_b32 s40, 0xc1980000
	s_mov_b32 s29, 0xc1c00000
	s_mov_b32 s28, 0xc1c80000
	s_mov_b32 s15, 0xc1d00000
	s_mov_b32 s14, 0xc1d80000
	s_branch .LBB0_140

; __device__ __forceinline__ unsigned cvtpk(float lo, float hi) { f32x2_t v = {lo, hi}; bf16x2_t b = __builtin_convertvector(v, bf16x2_t); return __builtin_bit_cast(unsigned, b); }
; #define LAS __attribute__((address_space(3)))
; #define MFMA32(a, b, c) __builtin_amdgcn_mfma_f32_32x32x16_bf16((a), (b), (c), 0, 0, 0)
; DI void ret_state_sweep(LAS unsigned char* lds, const bf16_t* MX, const bf16_t* VT, bf16_t* ST, int b, int hh, int dir, float lg, int wave) {
;     ...
;         for (int kb = 0; kb < 2; ++kb) {
;             f32x16 x;
; #pragma unroll
;             for (int i = 0; i < 16; ++i) x[i] = 0.f;
;             { bf16x8 af[8];
; #pragma unroll
;               for (int s = 0; s < 8; ++s) af[s] = *(const LAS bf16x8*)(Kl + kA + ((s * 32) ^ sx32) + kb * 8192);
; #pragma unroll
;               for (int s = 0; s < 8; ++s) x = MFMA32(af[s], qf[s], x); }
;             __builtin_amdgcn_sched_barrier(0);
;             const float d0 = dir ? (float)(kt * 64 + kb * 32 + 4 * h - tqf) : (float)(tqf - kt * 64 - kb * 32 - 4 * h);
; #pragma unroll
;             for (int i = 0; i < 16; ++i) { const float cr = (float)((i & 3) + 8 * (i >> 2)); x[i] *= __builtin_amdgcn_exp2f(lg * (dir ? d0 + cr : d0 - cr)); }
; #pragma unroll
;             for (int s2 = 0; s2 < 2; ++s2) {
;                 u32x4 pw; pw.x = cvtpk(x[8 * s2 + 0], x[8 * s2 + 1]); pw.y = cvtpk(x[8 * s2 + 2], x[8 * s2 + 3]); pw.z = cvtpk(x[8 * s2 + 4], x[8 * s2 + 5]); pw.w = cvtpk(x[8 * s2 + 6], x[8 * s2 + 7]);
;                 f4[2 * kb + s2] = __builtin_bit_cast(bf16x8, pw);
;             }
;             __builtin_amdgcn_sched_barrier(0);
;         }
; #pragma unroll
;         for (int f = 0; f < 4; ++f) {
;             const int vo = vA + ((f * 32) ^ mv16);
; #pragma unroll
;             for (int db = 0; db < 4; ++db) z[db] = MFMA32(f4[f], *(const LAS bf16x8*)(Vl + vo + db * 4096), z[db]);
.LBB0_140:
	v_cvt_f32_i32_e32 v114, v112
	v_add_f32_e32 v112, s68, v114
	v_add_f32_e32 v113, s62, v114
	v_mul_f32_e32 v112, v176, v112
	v_mul_f32_e32 v113, v176, v113
	v_exp_f32_e32 v112, v112
	v_exp_f32_e32 v113, v113
	s_nop 0
	v_pk_mul_f32 v[64:65], v[64:65], v[112:113]
	v_add_f32_e32 v112, s60, v114
	v_add_f32_e32 v113, s55, v114
	v_mul_f32_e32 v112, v176, v112
	v_mul_f32_e32 v113, v176, v113
	v_exp_f32_e32 v112, v112
	v_exp_f32_e32 v113, v113
	v_cvt_pk_bf16_f32 v116, v64, v65
	v_pk_mul_f32 v[66:67], v[66:67], v[112:113]
	v_add_f32_e32 v112, s52, v114
	v_add_f32_e32 v113, s49, v114
	v_mul_f32_e32 v112, v176, v112
	v_mul_f32_e32 v113, v176, v113
	v_exp_f32_e32 v112, v112
	v_exp_f32_e32 v113, v113
	v_cvt_pk_bf16_f32 v117, v66, v67
	v_pk_mul_f32 v[68:69], v[68:69], v[112:113]
	v_add_f32_e32 v112, s48, v114
	v_add_f32_e32 v113, s47, v114
	v_mul_f32_e32 v112, v176, v112
	v_mul_f32_e32 v113, v176, v113
	v_exp_f32_e32 v112, v112
	v_exp_f32_e32 v113, v113
	v_cvt_pk_bf16_f32 v118, v68, v69
	v_pk_mul_f32 v[70:71], v[70:71], v[112:113]
	v_add_f32_e32 v112, s46, v114
	v_add_f32_e32 v113, s43, v114
	v_mul_f32_e32 v112, v176, v112
	v_mul_f32_e32 v113, v176, v113
	v_exp_f32_e32 v112, v112
	v_exp_f32_e32 v113, v113
	v_cvt_pk_bf16_f32 v119, v70, v71
	v_pk_mul_f32 v[72:73], v[72:73], v[112:113]
	v_add_f32_e32 v112, s41, v114
	v_add_f32_e32 v113, s40, v114
	v_mul_f32_e32 v112, v176, v112
	v_mul_f32_e32 v113, v176, v113
	v_exp_f32_e32 v112, v112
	v_exp_f32_e32 v113, v113
	s_nop 0
	v_pk_mul_f32 v[74:75], v[74:75], v[112:113]
	v_add_f32_e32 v112, s29, v114
	v_add_f32_e32 v113, s28, v114
	v_mul_f32_e32 v112, v176, v112
	v_mul_f32_e32 v113, v176, v113
	v_exp_f32_e32 v112, v112
	v_exp_f32_e32 v113, v113
	s_nop 0
	v_pk_mul_f32 v[76:77], v[76:77], v[112:113]
	v_add_f32_e32 v112, s15, v114
	v_add_f32_e32 v113, s14, v114
	v_mul_f32_e32 v112, v176, v112
	v_mul_f32_e32 v113, v176, v113
	v_exp_f32_e32 v112, v112
	v_exp_f32_e32 v113, v113
	v_cvt_pk_bf16_f32 v114, v76, v77
	v_pk_mul_f32 v[78:79], v[78:79], v[112:113]
	v_cvt_pk_bf16_f32 v112, v72, v73
	v_cvt_pk_bf16_f32 v113, v74, v75
	v_cvt_pk_bf16_f32 v115, v78, v79
	s_waitcnt lgkmcnt(4)
	v_mfma_f32_32x32x16_bf16 v[64:79], v[218:221], v[80:83], 0
	ds_read_b128 v[218:221], v208 offset:8192
	s_waitcnt lgkmcnt(4)
	v_mfma_f32_32x32x16_bf16 v[64:79], v[222:225], v[84:87], v[64:79]
	ds_read_b128 v[222:225], v212 offset:8192
	s_waitcnt lgkmcnt(4)
	v_mfma_f32_32x32x16_bf16 v[64:79], v[226:229], v[88:91], v[64:79]
	ds_read_b128 v[226:229], v215 offset:8192
	s_waitcnt lgkmcnt(4)
	v_mfma_f32_32x32x16_bf16 v[64:79], v[230:233], v[92:95], v[64:79]
	ds_read_b128 v[230:233], v235 offset:16384
	s_waitcnt lgkmcnt(4)
	v_mfma_f32_32x32x16_bf16 v[64:79], v[246:249], v[96:99], v[64:79]
	ds_read_b128 v[246:249], v235 offset:20480
	s_waitcnt lgkmcnt(4)
	v_mfma_f32_32x32x16_bf16 v[64:79], v[218:221], v[100:103], v[64:79]
	ds_read_b128 v[218:221], v235 offset:24576
	s_waitcnt lgkmcnt(4)
	v_mfma_f32_32x32x16_bf16 v[64:79], v[222:225], v[104:107], v[64:79]
	ds_read_b128 v[222:225], v235 offset:28672
	s_waitcnt lgkmcnt(4)
	v_mfma_f32_32x32x16_bf16 v[64:79], v[226:229], v[108:111], v[64:79]
	ds_read_b128 v[226:229], v250 offset:16384
	s_or_b32 s61, s61, 0xdf
	v_readlane_b32 s22, v254, 18
	v_add_u32_e32 v206, 32, v217
	v_sub_u32_e32 v207, s61, v216
	v_readlane_b32 s23, v254, 19
	s_nop 1
	v_cndmask_b32_e64 v206, v206, v207, s[22:23]
	v_cvt_f32_i32_e32 v208, v206
	v_add_f32_e32 v206, s68, v208
	v_add_f32_e32 v207, s62, v208
	v_mul_f32_e32 v206, v176, v206
	v_mul_f32_e32 v207, v176, v207
	v_exp_f32_e32 v206, v206
	v_exp_f32_e32 v207, v207
	s_nop 0
	v_pk_mul_f32 v[64:65], v[206:207], v[64:65]
	v_add_f32_e32 v206, s60, v208
	v_add_f32_e32 v207, s55, v208
	v_mul_f32_e32 v206, v176, v206
	v_mul_f32_e32 v207, v176, v207
	v_exp_f32_e32 v206, v206
	v_exp_f32_e32 v207, v207
	v_cvt_pk_bf16_f32 v64, v64, v65
	v_pk_mul_f32 v[66:67], v[206:207], v[66:67]
	v_add_f32_e32 v206, s52, v208
	v_add_f32_e32 v207, s49, v208
	v_mul_f32_e32 v206, v176, v206
	v_mul_f32_e32 v207, v176, v207
	v_exp_f32_e32 v206, v206
	v_exp_f32_e32 v207, v207
	v_cvt_pk_bf16_f32 v65, v66, v67
	v_pk_mul_f32 v[68:69], v[206:207], v[68:69]
	v_add_f32_e32 v206, s48, v208
	v_add_f32_e32 v207, s47, v208
	v_mul_f32_e32 v206, v176, v206
	v_mul_f32_e32 v207, v176, v207
	v_exp_f32_e32 v206, v206
	v_exp_f32_e32 v207, v207
	v_cvt_pk_bf16_f32 v66, v68, v69
	v_pk_mul_f32 v[70:71], v[206:207], v[70:71]
	v_add_f32_e32 v206, s46, v208
	v_add_f32_e32 v207, s43, v208
	v_mul_f32_e32 v206, v176, v206
	v_mul_f32_e32 v207, v176, v207
	v_exp_f32_e32 v206, v206
	v_exp_f32_e32 v207, v207
	v_cvt_pk_bf16_f32 v67, v70, v71
	v_pk_mul_f32 v[72:73], v[206:207], v[72:73]
	v_add_f32_e32 v206, s41, v208
	v_add_f32_e32 v207, s40, v208
	v_mul_f32_e32 v206, v176, v206
	v_mul_f32_e32 v207, v176, v207
	v_exp_f32_e32 v206, v206
	v_exp_f32_e32 v207, v207
	v_cvt_pk_bf16_f32 v68, v72, v73
	v_pk_mul_f32 v[74:75], v[206:207], v[74:75]
	v_add_f32_e32 v206, s29, v208
	v_add_f32_e32 v207, s28, v208
	v_mul_f32_e32 v206, v176, v206
	v_mul_f32_e32 v207, v176, v207
	v_exp_f32_e32 v206, v206
	v_exp_f32_e32 v207, v207
	v_cvt_pk_bf16_f32 v69, v74, v75
	v_pk_mul_f32 v[76:77], v[206:207], v[76:77]
	v_add_f32_e32 v206, s15, v208
	v_add_f32_e32 v207, s14, v208
	v_mul_f32_e32 v206, v176, v206
	v_mul_f32_e32 v207, v176, v207
	v_exp_f32_e32 v206, v206
	v_exp_f32_e32 v207, v207
	v_cvt_pk_bf16_f32 v70, v76, v77
	v_pk_mul_f32 v[78:79], v[206:207], v[78:79]
	s_nop 0
	v_cvt_pk_bf16_f32 v71, v78, v79
	ds_read_b128 v[72:75], v250 offset:20480
	ds_read_b128 v[76:79], v250 offset:24576
	s_waitcnt lgkmcnt(6)
; #define LAS __attribute__((address_space(3)))
; #define MFMA32(a, b, c) __builtin_amdgcn_mfma_f32_32x32x16_bf16((a), (b), (c), 0, 0, 0)
; DI void ret_state_sweep(LAS unsigned char* lds, const bf16_t* MX, const bf16_t* VT, bf16_t* ST, int b, int hh, int dir, float lg, int wave) {
;     ...
; #pragma unroll
;         for (int f = 0; f < 4; ++f) {
;             const int vo = vA + ((f * 32) ^ mv16);
; #pragma unroll
;             for (int db = 0; db < 4; ++db) z[db] = MFMA32(f4[f], *(const LAS bf16x8*)(Vl + vo + db * 4096), z[db]);
;             __builtin_amdgcn_sched_barrier(0);
;         }
;         if ((it & 3) == 3) {
	v_mfma_f32_32x32x16_bf16 v[32:47], v[116:119], v[230:233], v[32:47]
	ds_read_b128 v[230:233], v250 offset:28672
	s_waitcnt lgkmcnt(6)
	v_mfma_f32_32x32x16_bf16 v[48:63], v[116:119], v[246:249], v[48:63]
	ds_read_b128 v[246:249], v252 offset:16384
	s_waitcnt lgkmcnt(6)
	v_mfma_f32_32x32x16_bf16 v[16:31], v[116:119], v[218:221], v[16:31]
	ds_read_b128 v[218:221], v252 offset:20480
	s_waitcnt lgkmcnt(6)
	v_mfma_f32_32x32x16_bf16 v[0:15], v[116:119], v[222:225], v[0:15]
	ds_read_b128 v[222:225], v252 offset:24576
	s_waitcnt lgkmcnt(6)
	v_mfma_f32_32x32x16_bf16 v[32:47], v[112:115], v[226:229], v[32:47]
	ds_read_b128 v[226:229], v252 offset:28672
	s_waitcnt lgkmcnt(6)
	v_mfma_f32_32x32x16_bf16 v[48:63], v[112:115], v[72:75], v[48:63]
	ds_read_b128 v[72:75], v253 offset:16384
	s_waitcnt lgkmcnt(6)
	v_mfma_f32_32x32x16_bf16 v[16:31], v[112:115], v[76:79], v[16:31]
	ds_read_b128 v[76:79], v253 offset:20480
	s_waitcnt lgkmcnt(6)
	v_mfma_f32_32x32x16_bf16 v[0:15], v[112:115], v[230:233], v[0:15]
	ds_read_b128 v[230:233], v253 offset:24576
	s_waitcnt lgkmcnt(6)
	v_mfma_f32_32x32x16_bf16 v[32:47], v[64:67], v[246:249], v[32:47]
	ds_read_b128 v[246:249], v253 offset:28672
	s_waitcnt lgkmcnt(6)
	v_mfma_f32_32x32x16_bf16 v[48:63], v[64:67], v[218:221], v[48:63]
	s_waitcnt lgkmcnt(5)
	v_mfma_f32_32x32x16_bf16 v[16:31], v[64:67], v[222:225], v[16:31]
	s_waitcnt lgkmcnt(4)
	v_mfma_f32_32x32x16_bf16 v[0:15], v[64:67], v[226:229], v[0:15]
	s_waitcnt lgkmcnt(3)
	v_mfma_f32_32x32x16_bf16 v[32:47], v[68:71], v[72:75], v[32:47]
	s_waitcnt lgkmcnt(2)
	v_mfma_f32_32x32x16_bf16 v[48:63], v[68:71], v[76:79], v[48:63]
	s_waitcnt lgkmcnt(1)
	v_mfma_f32_32x32x16_bf16 v[16:31], v[68:71], v[230:233], v[16:31]
	s_waitcnt lgkmcnt(0)
	v_mfma_f32_32x32x16_bf16 v[0:15], v[68:71], v[246:249], v[0:15]
	s_cmp_lg_u32 s5, 3
	s_cbranch_scc1 .LBB0_130
; __device__ __forceinline__ unsigned cvtpk(float lo, float hi) { f32x2_t v = {lo, hi}; bf16x2_t b = __builtin_convertvector(v, bf16x2_t); return __builtin_bit_cast(unsigned, b); }
; DI void ret_state_sweep(LAS unsigned char* lds, const bf16_t* MX, const bf16_t* VT, bf16_t* ST, int b, int hh, int dir, float lg, int wave) {
;     ...
;         if ((it & 3) == 3) {
;             bf16_t* sp = ST + ((size_t)(((b * 4 + hh) * 8) + n) << 16) + (size_t)(dvh * 128 + r) * 256 + dir * 128 + 32 * dkg + 4 * h;
; #pragma unroll
;             for (int db = 0; db < 4; ++db) {
; #pragma unroll
;                 for (int i = 0; i < 16; ++i) { R[db][i] = R[db][i] * g256 + z[db][i]; z[db][i] = 0.f; }
; #pragma unroll
;                 for (int g = 0; g < 4; ++g) { u32x2 w; w.x = cvtpk(R[db][4 * g + 0], R[db][4 * g + 1]); w.y = cvtpk(R[db][4 * g + 2], R[db][4 * g + 3]);
;                     *(u32x2*)(sp + (size_t)(db * 32) * 256 + 8 * g) = w; }
;             }
	v_readlane_b32 s5, v254, 24
	s_add_i32 s4, s5, s4
	s_lshl_b32 s62, s4, 17
	v_lshl_add_u64 v[64:65], v[124:125], 0, s[62:63]
	v_pk_fma_f32 v[174:175], v[120:121], v[174:175], v[32:33]
	v_pk_fma_f32 v[178:179], v[120:121], v[178:179], v[34:35]
	s_movk_i32 s4, 0x4000
	v_pk_fma_f32 v[180:181], v[120:121], v[180:181], v[36:37]
	v_pk_fma_f32 v[182:183], v[120:121], v[182:183], v[38:39]
	v_cvt_pk_bf16_f32 v32, v174, v175
	v_cvt_pk_bf16_f32 v33, v178, v179
	v_add_co_u32_e32 v34, vcc, s4, v64
	v_pk_fma_f32 v[184:185], v[120:121], v[184:185], v[40:41]
	v_pk_fma_f32 v[186:187], v[120:121], v[186:187], v[42:43]
	flat_store_dwordx2 v[64:65], v[32:33]
	v_cvt_pk_bf16_f32 v32, v180, v181
	v_cvt_pk_bf16_f32 v33, v182, v183
	v_addc_co_u32_e32 v35, vcc, 0, v65, vcc
	s_mov_b32 s4, 0x8000
	v_pk_fma_f32 v[188:189], v[120:121], v[188:189], v[44:45]
	v_pk_fma_f32 v[190:191], v[120:121], v[190:191], v[46:47]
	flat_store_dwordx2 v[64:65], v[32:33] offset:16
	v_cvt_pk_bf16_f32 v32, v184, v185
	v_cvt_pk_bf16_f32 v33, v186, v187
	v_pk_fma_f32 v[144:145], v[120:121], v[144:145], v[18:19]
	v_add_co_u32_e32 v18, vcc, s4, v64
	flat_store_dwordx2 v[64:65], v[32:33] offset:32
	v_cvt_pk_bf16_f32 v32, v188, v189
	v_cvt_pk_bf16_f32 v33, v190, v191
	v_pk_fma_f32 v[158:159], v[120:121], v[158:159], v[48:49]
	v_pk_fma_f32 v[160:161], v[120:121], v[160:161], v[50:51]
	v_addc_co_u32_e32 v19, vcc, 0, v65, vcc
	s_mov_b32 s4, 0xc000
	flat_store_dwordx2 v[64:65], v[32:33] offset:48
	v_pk_fma_f32 v[162:163], v[120:121], v[162:163], v[52:53]
	v_pk_fma_f32 v[164:165], v[120:121], v[164:165], v[54:55]
	v_cvt_pk_bf16_f32 v32, v158, v159
	v_cvt_pk_bf16_f32 v33, v160, v161
	v_pk_fma_f32 v[142:143], v[120:121], v[142:143], v[16:17]
	v_pk_fma_f32 v[126:127], v[120:121], v[126:127], v[0:1]
	v_pk_fma_f32 v[128:129], v[120:121], v[128:129], v[2:3]
	v_add_co_u32_e32 v2, vcc, s4, v64
	v_pk_fma_f32 v[166:167], v[120:121], v[166:167], v[56:57]
	v_pk_fma_f32 v[168:169], v[120:121], v[168:169], v[58:59]
	flat_store_dwordx2 v[34:35], v[32:33]
	v_cvt_pk_bf16_f32 v32, v162, v163
	v_cvt_pk_bf16_f32 v33, v164, v165
	v_pk_fma_f32 v[146:147], v[120:121], v[146:147], v[20:21]
	v_pk_fma_f32 v[148:149], v[120:121], v[148:149], v[22:23]
	v_cvt_pk_bf16_f32 v16, v142, v143
	v_cvt_pk_bf16_f32 v17, v144, v145
	v_pk_fma_f32 v[130:131], v[120:121], v[130:131], v[4:5]
	v_pk_fma_f32 v[132:133], v[120:121], v[132:133], v[6:7]
	v_cvt_pk_bf16_f32 v0, v126, v127
	v_cvt_pk_bf16_f32 v1, v128, v129
	v_addc_co_u32_e32 v3, vcc, 0, v65, vcc
	v_pk_fma_f32 v[170:171], v[120:121], v[170:171], v[60:61]
	v_pk_fma_f32 v[172:173], v[120:121], v[172:173], v[62:63]
	flat_store_dwordx2 v[34:35], v[32:33] offset:16
	v_cvt_pk_bf16_f32 v32, v166, v167
	v_cvt_pk_bf16_f32 v33, v168, v169
	v_pk_fma_f32 v[150:151], v[120:121], v[150:151], v[24:25]
	v_pk_fma_f32 v[152:153], v[120:121], v[152:153], v[26:27]
	flat_store_dwordx2 v[18:19], v[16:17]
	v_cvt_pk_bf16_f32 v16, v146, v147
	v_cvt_pk_bf16_f32 v17, v148, v149
	v_pk_fma_f32 v[134:135], v[120:121], v[134:135], v[8:9]
	v_pk_fma_f32 v[136:137], v[120:121], v[136:137], v[10:11]
	flat_store_dwordx2 v[2:3], v[0:1]
	v_cvt_pk_bf16_f32 v0, v130, v131
	v_cvt_pk_bf16_f32 v1, v132, v133
	flat_store_dwordx2 v[34:35], v[32:33] offset:32
	v_cvt_pk_bf16_f32 v32, v170, v171
	v_cvt_pk_bf16_f32 v33, v172, v173
	v_pk_fma_f32 v[154:155], v[120:121], v[154:155], v[28:29]
	v_pk_fma_f32 v[156:157], v[120:121], v[156:157], v[30:31]
	flat_store_dwordx2 v[18:19], v[16:17] offset:16
	v_cvt_pk_bf16_f32 v16, v150, v151
	v_cvt_pk_bf16_f32 v17, v152, v153
	v_pk_fma_f32 v[138:139], v[120:121], v[138:139], v[12:13]
	v_pk_fma_f32 v[140:141], v[120:121], v[140:141], v[14:15]
	flat_store_dwordx2 v[2:3], v[0:1] offset:16
	v_cvt_pk_bf16_f32 v0, v134, v135
	v_cvt_pk_bf16_f32 v1, v136, v137
	flat_store_dwordx2 v[34:35], v[32:33] offset:48
	flat_store_dwordx2 v[18:19], v[16:17] offset:32
	v_cvt_pk_bf16_f32 v16, v154, v155
	v_cvt_pk_bf16_f32 v17, v156, v157
	flat_store_dwordx2 v[2:3], v[0:1] offset:32
	v_cvt_pk_bf16_f32 v0, v138, v139
	v_cvt_pk_bf16_f32 v1, v140, v141
	v_mov_b32_e32 v32, 0
	flat_store_dwordx2 v[18:19], v[16:17] offset:48
	flat_store_dwordx2 v[2:3], v[0:1] offset:48
	v_mov_b32_e32 v33, v32
	v_mov_b32_e32 v34, v32
	v_mov_b32_e32 v35, v32
	v_mov_b32_e32 v36, v32
	v_mov_b32_e32 v37, v32
	v_mov_b32_e32 v38, v32
	v_mov_b32_e32 v39, v32
	v_mov_b32_e32 v40, v32
	v_mov_b32_e32 v41, v32
	v_mov_b32_e32 v42, v32
	v_mov_b32_e32 v43, v32
	v_mov_b32_e32 v44, v32
	v_mov_b32_e32 v45, v32
	v_mov_b32_e32 v46, v32
	v_mov_b32_e32 v47, v32
	v_mov_b32_e32 v48, v32
	v_mov_b32_e32 v49, v32
	v_mov_b32_e32 v50, v32
	v_mov_b32_e32 v51, v32
	v_mov_b32_e32 v52, v32
	v_mov_b32_e32 v53, v32
	v_mov_b32_e32 v54, v32
	v_mov_b32_e32 v55, v32
	v_mov_b32_e32 v56, v32
	v_mov_b32_e32 v57, v32
	v_mov_b32_e32 v58, v32
	v_mov_b32_e32 v59, v32
	v_mov_b32_e32 v60, v32
	v_mov_b32_e32 v61, v32
	v_mov_b32_e32 v62, v32
	v_mov_b32_e32 v63, v32
	v_mov_b32_e32 v16, v32
	v_mov_b32_e32 v17, v32
	v_mov_b32_e32 v18, v32
	v_mov_b32_e32 v19, v32
	v_mov_b32_e32 v20, v32
	v_mov_b32_e32 v21, v32
	v_mov_b32_e32 v22, v32
	v_mov_b32_e32 v23, v32
	v_mov_b32_e32 v24, v32
	v_mov_b32_e32 v25, v32
	v_mov_b32_e32 v26, v32
	v_mov_b32_e32 v27, v32
	v_mov_b32_e32 v28, v32
	v_mov_b32_e32 v29, v32
	v_mov_b32_e32 v30, v32
	v_mov_b32_e32 v31, v32
	v_mov_b32_e32 v0, v32
	v_mov_b32_e32 v1, v32
	v_mov_b32_e32 v2, v32
	v_mov_b32_e32 v3, v32
	v_mov_b32_e32 v4, v32
	v_mov_b32_e32 v5, v32
	v_mov_b32_e32 v6, v32
	v_mov_b32_e32 v7, v32
	v_mov_b32_e32 v8, v32
	v_mov_b32_e32 v9, v32
	v_mov_b32_e32 v10, v32
	v_mov_b32_e32 v11, v32
	v_mov_b32_e32 v12, v32
	v_mov_b32_e32 v13, v32
	v_mov_b32_e32 v14, v32
	v_mov_b32_e32 v15, v32
	s_branch .LBB0_130
